# final rmsnorm phase: packed fp32 multiplies split into scalar pairs
# speedup vs baseline: 1.0042x; 1.0031x over previous
; __device__ __forceinline__ void p7d_final(Frame& F) {
;     ...
;     for (int t = gw; t < NT_TOK; t += NGW) {
;         const float sp = (lane < 16) ? SS3[(size_t)t * 16 + lane] : 0.f; const float r3 = 1.0f / sqrtf(wave_sum(sp) * (1.0f / DM) + RMS_EPS);
;         const v4u* xin = (const v4u*)((const bf16*)(F.ws + WS_X2B) + (size_t)t * DM) + lane;
;         f32x4* row = (f32x4*)(F.out + (size_t)t * DM);
;         v4u v[4];
; #pragma unroll
;         for (int j = 0; j < 4; ++j) v[j] = xin[64 * j];
; #pragma unroll
;         for (int j = 0; j < 4; ++j) {
;             const f32x4 a = (f32x4){bflo(v[j].x), bfhi(v[j].x), bflo(v[j].y), bfhi(v[j].y)} * r3 * gf[2 * j], b = (f32x4){bflo(v[j].z), bfhi(v[j].z), bflo(v[j].w), bfhi(v[j].w)} * r3 * gf[2 * j + 1];
;             row[128 * j + 2 * lane] = a; row[128 * j + 2 * lane + 1] = b; }
.LBB0_1148:
	s_or_b64 exec, exec, s[2:3]
	v_lshl_add_u64 v[48:49], s[66:67], 0, v[34:35]
	v_add_co_u32_e32 v60, vcc, s11, v48
	s_waitcnt vmcnt(0)
	ds_bpermute_b32 v47, v38, v46
	v_addc_co_u32_e32 v61, vcc, 0, v49, vcc
	global_load_dwordx4 v[48:51], v[60:61], off
	global_load_dwordx4 v[52:55], v[60:61], off offset:1024
	global_load_dwordx4 v[56:59], v[60:61], off offset:2048
	s_waitcnt lgkmcnt(0)
	v_add_f32_e32 v46, v46, v47
	global_load_dwordx4 v[60:63], v[60:61], off offset:3072
	ds_bpermute_b32 v47, v39, v46
	s_add_i32 s30, s30, s34
	v_lshl_add_u64 v[32:33], v[32:33], 0, s[4:5]
	v_lshl_add_u64 v[34:35], v[34:35], 0, s[6:7]
	s_cmpk_lt_i32 s30, 0x6000
	s_waitcnt lgkmcnt(0)
	v_add_f32_e32 v46, v46, v47
	ds_bpermute_b32 v47, v40, v46
	s_waitcnt lgkmcnt(0)
	v_add_f32_e32 v46, v46, v47
	ds_bpermute_b32 v47, v41, v46
	s_waitcnt lgkmcnt(0)
	v_add_f32_e32 v46, v46, v47
	ds_bpermute_b32 v47, v42, v46
	s_waitcnt lgkmcnt(0)
	v_add_f32_e32 v46, v46, v47
	ds_bpermute_b32 v47, v43, v46
	s_waitcnt lgkmcnt(0)
	v_add_f32_e32 v46, v46, v47
	v_fmamk_f32 v46, v46, 0x3a000000, v44
	v_mul_f32_e32 v47, 0x4f800000, v46
	v_cmp_gt_f32_e32 vcc, s10, v46
	s_waitcnt vmcnt(2)
	v_lshlrev_b32_e32 v68, 16, v54
	v_cndmask_b32_e32 v46, v46, v47, vcc
	v_sqrt_f32_e32 v47, v46
	v_and_b32_e32 v69, 0xffff0000, v54
	v_lshlrev_b32_e32 v54, 16, v55
	v_and_b32_e32 v55, 0xffff0000, v55
	v_add_u32_e32 v64, -1, v47
	v_add_u32_e32 v65, 1, v47
	v_fma_f32 v66, -v64, v47, v46
	v_fma_f32 v67, -v65, v47, v46
	v_cmp_ge_f32_e64 s[2:3], 0, v66
	s_nop 1
	v_cndmask_b32_e64 v47, v47, v64, s[2:3]
	v_cmp_lt_f32_e64 s[2:3], 0, v67
	s_nop 1
	v_cndmask_b32_e64 v47, v47, v65, s[2:3]
	v_mul_f32_e32 v64, 0x37800000, v47
	v_cndmask_b32_e32 v47, v47, v64, vcc
	v_cmp_class_f32_e32 vcc, v46, v45
	s_nop 1
	v_cndmask_b32_e32 v46, v47, v46, vcc
	v_div_scale_f32 v47, s[2:3], v46, v46, 1.0
	v_rcp_f32_e32 v64, v47
	v_div_scale_f32 v65, vcc, 1.0, v46, 1.0
	v_fma_f32 v66, -v47, v64, 1.0
	v_fmac_f32_e32 v64, v66, v64
	v_mul_f32_e32 v66, v65, v64
	v_fma_f32 v67, -v47, v66, v65
	v_fmac_f32_e32 v66, v67, v64
	v_fma_f32 v47, -v47, v66, v65
	v_div_fmas_f32 v47, v47, v64, v66
	v_div_fixup_f32 v72, v47, v46, 1.0
	v_lshlrev_b32_e32 v46, 16, v48
	v_and_b32_e32 v47, 0xffff0000, v48
	v_lshlrev_b32_e32 v48, 16, v49
	v_and_b32_e32 v49, 0xffff0000, v49
	v_lshlrev_b32_e32 v64, 16, v50
	v_and_b32_e32 v65, 0xffff0000, v50
	v_lshlrev_b32_e32 v50, 16, v51
	v_and_b32_e32 v51, 0xffff0000, v51
	v_lshlrev_b32_e32 v66, 16, v52
	v_and_b32_e32 v67, 0xffff0000, v52
	v_lshlrev_b32_e32 v52, 16, v53
	v_and_b32_e32 v53, 0xffff0000, v53
	v_mul_f32_e32 v46, v72, v46
	v_mul_f32_e32 v47, v72, v47
	v_mul_f32_e32 v48, v72, v48
	v_mul_f32_e32 v49, v72, v49
	v_mul_f32_e32 v64, v72, v64
	v_mul_f32_e32 v65, v72, v65
	v_mul_f32_e32 v50, v72, v50
	v_mul_f32_e32 v51, v72, v51
	v_mul_f32_e32 v70, v72, v66
	v_mul_f32_e32 v71, v72, v67
	v_mul_f32_e32 v66, v72, v52
	v_mul_f32_e32 v67, v72, v53
	v_mul_f32_e32 v68, v72, v68
	v_mul_f32_e32 v69, v72, v69
	v_mul_f32_e32 v54, v72, v54
	v_mul_f32_e32 v55, v72, v55
	v_mul_f32_e32 v48, v6, v48
	v_mul_f32_e32 v49, v7, v49
	v_mul_f32_e32 v46, v4, v46
	v_mul_f32_e32 v47, v5, v47
	v_mul_f32_e32 v52, v2, v50
	v_mul_f32_e32 v53, v3, v51
	v_mul_f32_e32 v50, v0, v64
	v_mul_f32_e32 v51, v1, v65
	v_mul_f32_e32 v66, v14, v66
	v_mul_f32_e32 v67, v15, v67
	v_mul_f32_e32 v64, v12, v70
	v_mul_f32_e32 v65, v13, v71
	v_mul_f32_e32 v70, v10, v54
	v_mul_f32_e32 v71, v11, v55
	v_mul_f32_e32 v68, v8, v68
	v_mul_f32_e32 v69, v9, v69
	global_store_dwordx4 v[36:37], v[46:49], off offset:-4096
	global_store_dwordx4 v[36:37], v[50:53], off offset:-4080
	global_store_dwordx4 v[36:37], v[64:67], off offset:-2048
	global_store_dwordx4 v[36:37], v[68:71], off offset:-2032
	s_waitcnt vmcnt(5)
	v_lshlrev_b32_e32 v46, 16, v56
	v_and_b32_e32 v47, 0xffff0000, v56
	v_lshlrev_b32_e32 v48, 16, v57
	v_and_b32_e32 v49, 0xffff0000, v57
	v_mul_f32_e32 v46, v72, v46
	v_mul_f32_e32 v47, v72, v47
	v_mul_f32_e32 v48, v72, v48
	v_mul_f32_e32 v49, v72, v49
	v_lshlrev_b32_e32 v50, 16, v58
	v_and_b32_e32 v51, 0xffff0000, v58
	v_lshlrev_b32_e32 v52, 16, v59
	v_and_b32_e32 v53, 0xffff0000, v59
	v_mul_f32_e32 v48, v18, v48
	v_mul_f32_e32 v49, v19, v49
	v_mul_f32_e32 v46, v16, v46
	v_mul_f32_e32 v47, v17, v47
	v_mul_f32_e32 v50, v72, v50
	v_mul_f32_e32 v51, v72, v51
	v_mul_f32_e32 v52, v72, v52
	v_mul_f32_e32 v53, v72, v53
	v_mul_f32_e32 v52, v22, v52
	v_mul_f32_e32 v53, v23, v53
	v_mul_f32_e32 v50, v20, v50
	v_mul_f32_e32 v51, v21, v51
	global_store_dwordx4 v[36:37], v[46:49], off
	global_store_dwordx4 v[36:37], v[50:53], off offset:16
	s_waitcnt vmcnt(6)
	v_lshlrev_b32_e32 v46, 16, v60
	v_and_b32_e32 v47, 0xffff0000, v60
	v_lshlrev_b32_e32 v48, 16, v61
	v_and_b32_e32 v49, 0xffff0000, v61
	v_mul_f32_e32 v46, v72, v46
	v_mul_f32_e32 v47, v72, v47
	v_mul_f32_e32 v48, v72, v48
	v_mul_f32_e32 v49, v72, v49
	v_lshlrev_b32_e32 v50, 16, v62
	v_and_b32_e32 v51, 0xffff0000, v62
	v_lshlrev_b32_e32 v52, 16, v63
	v_and_b32_e32 v53, 0xffff0000, v63
	v_mul_f32_e32 v48, v26, v48
	v_mul_f32_e32 v49, v27, v49
	v_mul_f32_e32 v46, v24, v46
	v_mul_f32_e32 v47, v25, v47
	v_mul_f32_e32 v50, v72, v50
	v_mul_f32_e32 v51, v72, v51
	v_mul_f32_e32 v52, v72, v52
	v_mul_f32_e32 v53, v72, v53
	v_mul_f32_e32 v52, v30, v52
	v_mul_f32_e32 v53, v31, v53
	v_mul_f32_e32 v50, v28, v50
	v_mul_f32_e32 v51, v29, v51
	global_store_dwordx4 v[36:37], v[46:49], off offset:2048
	global_store_dwordx4 v[36:37], v[50:53], off offset:2064
	v_lshl_add_u64 v[36:37], v[36:37], 0, s[8:9]
	s_cbranch_scc0 .LBB0_1151
